# v168 with the phase C item deal also aligned to the XCD whose workgroups read those D1 rows in the FFT GEMM
# speedup vs baseline: 1.0277x; 1.0015x over previous
.LBB0_576:
	s_andn2_b64 vcc, exec, s[12:13]
	s_cbranch_vccnz .LBB0_578
	s_bfe_u32 s88, s22, 0x10002
	s_lshl_b32 s88, s88, 7
	s_and_b32 s16, s22, 3
	s_lshl_b32 s16, s16, 5
	s_or_b32 s88, s88, s16
	s_bfe_u32 s16, s22, 0x10003
	s_lshl_b32 s16, s16, 4
	s_or_b32 s88, s88, s16
	s_lshr_b32 s16, s22, 4
	s_or_b32 s88, s88, s16
	s_cmpk_eq_i32 s23, 0x100
	s_cselect_b32 s88, s88, s22
	s_ashr_i32 s16, s88, 7
	s_and_b32 s12, s88, 15
	s_lshl_b32 s17, s16, 13
	s_lshl_b32 s18, s12, 9
	s_lshr_b32 s13, s88, 4
	s_or_b32 s17, s17, s18
	s_lshl_b32 s12, s12, 3
	s_movk_i32 s28, 0x1000
	s_branch .LBB0_579
